# grid barrier: non-leader workgroups poll the global generation word directly (one release hop less); on top of batched stats_rows
# baseline (speedup 1.0000x reference)
.LBB0_62:
	s_or_b64 exec, exec, s[16:17]
	v_cvt_f32_u32_e32 v4, v2
	s_waitcnt vmcnt(0)
	v_readfirstlane_b32 s3, v3
	v_sub_u32_e32 v3, 0, v2
	v_rcp_iflag_f32_e32 v4, v4
	v_add_u32_e32 v5, s3, v1
	v_mul_f32_e32 v4, 0x4f7ffffe, v4
	v_cvt_u32_f32_e32 v4, v4
	v_mul_lo_u32 v1, v3, v4
	v_mul_hi_u32 v1, v4, v1
	v_add_u32_e32 v1, v4, v1
	v_mul_hi_u32 v1, v5, v1
	v_mul_lo_u32 v3, v1, v2
	v_sub_u32_e32 v3, v5, v3
	v_add_u32_e32 v4, 1, v1
	v_cmp_ge_u32_e32 vcc, v3, v2
	s_nop 1
	v_cndmask_b32_e32 v1, v1, v4, vcc
	v_sub_u32_e32 v4, v3, v2
	v_cndmask_b32_e32 v3, v3, v4, vcc
	v_add_u32_e32 v4, 1, v1
	v_cmp_ge_u32_e32 vcc, v3, v2
	v_add_u32_e32 v3, 1, v5
	s_nop 0
	v_cndmask_b32_e32 v1, v1, v4, vcc
	v_mul_lo_u32 v4, v2, v1
	v_add_u32_e32 v2, v4, v2
	v_cmp_ne_u32_e32 vcc, v3, v2
	s_and_saveexec_b64 s[10:11], vcc
	s_xor_b64 s[14:15], exec, s[10:11]
	s_cbranch_execz .LBB0_76
	s_waitcnt lgkmcnt(0)
	s_add_u32 s20, s70, 0x3ac97500
	s_addc_u32 s21, s71, 0
	v_mov_b32_e32 v0, 0
	global_load_dword v0, v0, s[20:21] sc1
	s_waitcnt vmcnt(0)
	v_cmp_eq_u32_e32 vcc, v0, v1
	s_and_saveexec_b64 s[16:17], vcc
	s_cbranch_execz .LBB0_75
	s_add_u32 s18, s70, 0x3ac94200
	s_addc_u32 s19, s71, 0
	s_mov_b32 s3, 1
	s_mov_b64 s[22:23], 0
	v_mov_b32_e32 v0, 0
	s_branch .LBB0_66

.LBB0_119:
	s_lshl_b32 s1, s81, 8
	s_add_u32 s6, s8, s1
	s_addc_u32 s7, s9, 0
	v_mov_b32_e32 v1, 0x1000
	v_mov_b32_e32 v3, 1
	global_atomic_add v3, v1, v3, s[6:7] offset:1024 sc0
	v_cvt_f32_u32_e32 v1, v2
	v_sub_u32_e32 v4, 0, v2
	v_rcp_iflag_f32_e32 v1, v1
	s_nop 0
	v_mul_f32_e32 v1, 0x4f7ffffe, v1
	v_cvt_u32_f32_e32 v1, v1
	v_mul_lo_u32 v4, v4, v1
	v_mul_hi_u32 v4, v1, v4
	v_add_u32_e32 v1, v1, v4
	s_waitcnt vmcnt(0)
	v_mul_hi_u32 v1, v3, v1
	v_mul_lo_u32 v4, v1, v2
	v_sub_u32_e32 v4, v3, v4
	v_add_u32_e32 v5, 1, v1
	v_cmp_ge_u32_e32 vcc, v4, v2
	v_add_u32_e32 v3, 1, v3
	s_nop 0
	v_cndmask_b32_e32 v1, v1, v5, vcc
	v_sub_u32_e32 v5, v4, v2
	v_cndmask_b32_e32 v4, v4, v5, vcc
	v_add_u32_e32 v5, 1, v1
	v_cmp_ge_u32_e32 vcc, v4, v2
	s_nop 1
	v_cndmask_b32_e32 v1, v1, v5, vcc
	v_mul_lo_u32 v4, v2, v1
	v_add_u32_e32 v2, v4, v2
	v_cmp_ne_u32_e32 vcc, v3, v2
	s_and_saveexec_b64 s[10:11], vcc
	s_xor_b64 s[14:15], exec, s[10:11]
	s_cbranch_execz .LBB0_132
	s_waitcnt lgkmcnt(0)
	s_add_u32 s18, s8, 0x3500
	s_addc_u32 s19, s9, 0
	v_mov_b32_e32 v0, 0
	global_load_dword v0, v0, s[18:19] sc1
	s_waitcnt vmcnt(0)
	v_cmp_eq_u32_e32 vcc, v0, v1
	s_and_saveexec_b64 s[16:17], vcc
	s_cbranch_execz .LBB0_131
	s_mov_b32 s1, 1
	s_mov_b64 s[20:21], 0
	v_mov_b32_e32 v0, 0
	s_branch .LBB0_123

.LBB0_216:
	s_lshl_b32 s3, s81, 8
	s_add_u32 s4, s8, s3
	s_addc_u32 s5, s9, 0
	v_mov_b32_e32 v1, 0x1000
	v_mov_b32_e32 v3, 1
	global_atomic_add v3, v1, v3, s[4:5] offset:1024 sc0
	v_cvt_f32_u32_e32 v1, v2
	v_sub_u32_e32 v4, 0, v2
	v_rcp_iflag_f32_e32 v1, v1
	s_nop 0
	v_mul_f32_e32 v1, 0x4f7ffffe, v1
	v_cvt_u32_f32_e32 v1, v1
	v_mul_lo_u32 v4, v4, v1
	v_mul_hi_u32 v4, v1, v4
	v_add_u32_e32 v1, v1, v4
	s_waitcnt vmcnt(0)
	v_mul_hi_u32 v1, v3, v1
	v_mul_lo_u32 v4, v1, v2
	v_sub_u32_e32 v4, v3, v4
	v_add_u32_e32 v5, 1, v1
	v_cmp_ge_u32_e32 vcc, v4, v2
	v_add_u32_e32 v3, 1, v3
	s_nop 0
	v_cndmask_b32_e32 v1, v1, v5, vcc
	v_sub_u32_e32 v5, v4, v2
	v_cndmask_b32_e32 v4, v4, v5, vcc
	v_add_u32_e32 v5, 1, v1
	v_cmp_ge_u32_e32 vcc, v4, v2
	s_nop 1
	v_cndmask_b32_e32 v1, v1, v5, vcc
	v_mul_lo_u32 v4, v2, v1
	v_add_u32_e32 v2, v4, v2
	v_cmp_ne_u32_e32 vcc, v3, v2
	s_and_saveexec_b64 s[6:7], vcc
	s_xor_b64 s[6:7], exec, s[6:7]
	s_cbranch_execz .LBB0_229
	s_waitcnt lgkmcnt(0)
	s_add_u32 s18, s8, 0x3500
	s_addc_u32 s19, s9, 0
	v_mov_b32_e32 v0, 0
	global_load_dword v0, v0, s[18:19] sc1
	s_waitcnt vmcnt(0)
	v_cmp_eq_u32_e32 vcc, v0, v1
	s_and_saveexec_b64 s[16:17], vcc
	s_cbranch_execz .LBB0_228
	s_mov_b32 s3, 1
	s_mov_b64 s[20:21], 0
	v_mov_b32_e32 v0, 0
	s_branch .LBB0_220

.LBB0_313:
	s_or_b64 exec, exec, s[12:13]
	v_cvt_f32_u32_e32 v4, v2
	s_waitcnt vmcnt(0)
	v_readfirstlane_b32 s3, v3
	v_sub_u32_e32 v3, 0, v2
	v_rcp_iflag_f32_e32 v4, v4
	v_add_u32_e32 v5, s3, v1
	v_mul_f32_e32 v4, 0x4f7ffffe, v4
	v_cvt_u32_f32_e32 v4, v4
	v_mul_lo_u32 v1, v3, v4
	v_mul_hi_u32 v1, v4, v1
	v_add_u32_e32 v1, v4, v1
	v_mul_hi_u32 v1, v5, v1
	v_mul_lo_u32 v3, v1, v2
	v_sub_u32_e32 v3, v5, v3
	v_add_u32_e32 v4, 1, v1
	v_cmp_ge_u32_e32 vcc, v3, v2
	s_nop 1
	v_cndmask_b32_e32 v1, v1, v4, vcc
	v_sub_u32_e32 v4, v3, v2
	v_cndmask_b32_e32 v3, v3, v4, vcc
	v_add_u32_e32 v4, 1, v1
	v_cmp_ge_u32_e32 vcc, v3, v2
	v_add_u32_e32 v3, 1, v5
	s_nop 0
	v_cndmask_b32_e32 v1, v1, v4, vcc
	v_mul_lo_u32 v4, v2, v1
	v_add_u32_e32 v2, v4, v2
	v_cmp_ne_u32_e32 vcc, v3, v2
	s_and_saveexec_b64 s[8:9], vcc
	s_xor_b64 s[8:9], exec, s[8:9]
	s_cbranch_execz .LBB0_327
	s_waitcnt lgkmcnt(0)
	s_add_u32 s16, s70, 0x3ac97500
	s_addc_u32 s17, s71, 0
	v_mov_b32_e32 v0, 0
	global_load_dword v0, v0, s[16:17] sc1
	s_waitcnt vmcnt(0)
	v_cmp_eq_u32_e32 vcc, v0, v1
	s_and_saveexec_b64 s[12:13], vcc
	s_cbranch_execz .LBB0_326
	s_add_u32 s14, s70, 0x3ac94200
	s_addc_u32 s15, s71, 0
	s_mov_b32 s3, 1
	s_mov_b64 s[18:19], 0
	v_mov_b32_e32 v0, 0
	s_branch .LBB0_317

.LBB0_590:
	s_or_b64 exec, exec, s[14:15]
	v_cvt_f32_u32_e32 v4, v2
	s_waitcnt vmcnt(0)
	v_readfirstlane_b32 s3, v3
	v_sub_u32_e32 v3, 0, v2
	v_rcp_iflag_f32_e32 v4, v4
	v_add_u32_e32 v5, s3, v1
	v_mul_f32_e32 v4, 0x4f7ffffe, v4
	v_cvt_u32_f32_e32 v4, v4
	v_mul_lo_u32 v1, v3, v4
	v_mul_hi_u32 v1, v4, v1
	v_add_u32_e32 v1, v4, v1
	v_mul_hi_u32 v1, v5, v1
	v_mul_lo_u32 v3, v1, v2
	v_sub_u32_e32 v3, v5, v3
	v_add_u32_e32 v4, 1, v1
	v_cmp_ge_u32_e32 vcc, v3, v2
	s_nop 1
	v_cndmask_b32_e32 v1, v1, v4, vcc
	v_sub_u32_e32 v4, v3, v2
	v_cndmask_b32_e32 v3, v3, v4, vcc
	v_add_u32_e32 v4, 1, v1
	v_cmp_ge_u32_e32 vcc, v3, v2
	v_add_u32_e32 v3, 1, v5
	s_nop 0
	v_cndmask_b32_e32 v1, v1, v4, vcc
	v_mul_lo_u32 v4, v2, v1
	v_add_u32_e32 v2, v4, v2
	v_cmp_ne_u32_e32 vcc, v3, v2
	s_and_saveexec_b64 s[10:11], vcc
	s_xor_b64 s[12:13], exec, s[10:11]
	s_cbranch_execz .LBB0_604
	s_waitcnt lgkmcnt(0)
	s_add_u32 s18, s70, 0x3ac97500
	s_addc_u32 s19, s71, 0
	v_mov_b32_e32 v0, 0
	global_load_dword v0, v0, s[18:19] sc1
	s_waitcnt vmcnt(0)
	v_cmp_eq_u32_e32 vcc, v0, v1
	s_and_saveexec_b64 s[14:15], vcc
	s_cbranch_execz .LBB0_603
	s_add_u32 s16, s70, 0x3ac94200
	s_addc_u32 s17, s71, 0
	s_mov_b32 s3, 1
	s_mov_b64 s[20:21], 0
	v_mov_b32_e32 v0, 0
	s_branch .LBB0_594

.LBB0_719:
	s_or_b64 exec, exec, s[8:9]
	v_cvt_f32_u32_e32 v4, v2
	s_waitcnt vmcnt(0)
	v_readfirstlane_b32 s6, v3
	v_sub_u32_e32 v3, 0, v2
	v_rcp_iflag_f32_e32 v4, v4
	v_add_u32_e32 v5, s6, v1
	v_mul_f32_e32 v4, 0x4f7ffffe, v4
	v_cvt_u32_f32_e32 v4, v4
	v_mul_lo_u32 v1, v3, v4
	v_mul_hi_u32 v1, v4, v1
	v_add_u32_e32 v1, v4, v1
	v_mul_hi_u32 v1, v5, v1
	v_mul_lo_u32 v3, v1, v2
	v_sub_u32_e32 v3, v5, v3
	v_add_u32_e32 v4, 1, v1
	v_cmp_ge_u32_e32 vcc, v3, v2
	s_nop 1
	v_cndmask_b32_e32 v1, v1, v4, vcc
	v_sub_u32_e32 v4, v3, v2
	v_cndmask_b32_e32 v3, v3, v4, vcc
	v_add_u32_e32 v4, 1, v1
	v_cmp_ge_u32_e32 vcc, v3, v2
	v_add_u32_e32 v3, 1, v5
	s_nop 0
	v_cndmask_b32_e32 v1, v1, v4, vcc
	v_mul_lo_u32 v4, v2, v1
	v_add_u32_e32 v2, v4, v2
	v_cmp_ne_u32_e32 vcc, v3, v2
	s_and_saveexec_b64 s[6:7], vcc
	s_xor_b64 s[6:7], exec, s[6:7]
	s_cbranch_execz .LBB0_733
	s_waitcnt lgkmcnt(0)
	s_add_u32 s12, s70, 0x3ac97500
	s_addc_u32 s13, s71, 0
	v_mov_b32_e32 v0, 0
	global_load_dword v0, v0, s[12:13] sc1
	s_waitcnt vmcnt(0)
	v_cmp_eq_u32_e32 vcc, v0, v1
	s_and_saveexec_b64 s[8:9], vcc
	s_cbranch_execz .LBB0_732
	s_add_u32 s10, s70, 0x3ac94200
	s_addc_u32 s11, s71, 0
	s_mov_b32 s24, 1
	s_mov_b64 s[14:15], 0
	v_mov_b32_e32 v0, 0
	s_branch .LBB0_723
